# phase-0 weight-conversion tiles dealt round-robin across matrices (balanced 11 tiles per workgroup instead of 4..22)
# speedup vs baseline: 1.0010x; 1.0010x over previous
; #define LAS __attribute__((address_space(3)))
; __device__ __forceinline__ bf16_t* wl(PCP p, int i, size_t off) { return (bf16_t*)(p->ws + WS_W + (size_t)i * WL_STRIDE + off); }
; __device__ __forceinline__ void cvt_matrix(const float* W, int K, int N, bf16_t* Wt, const float* gk, int upperm, LAS float* tile, int bid, int G, int tid) {
;     const int nst = N / 256, ntiles = (K / 64) * nst;
;     for (int ti = bid; ti < ntiles; ti += G) {
;         const int kt = ti / nst, ns = ti % nst;
; __device__ __forceinline__ void phase0(PCP p, LAS unsigned char* lds, int bid, int G, int tid) {
;     ...
;     for (int i = 0; i < 4; ++i) {
;         const int j = i >> 1;
;         if ((i & 1) == 0) cvt_matrix(p->in[2] + (size_t)j * 1024 * 2048, 1024, 2048, wl(p, i, 0), p->in[1] + i * 1024, 3, tile, bid, G, tid);
;         else              cvt_matrix(p->in[15] + (size_t)j * 1024 * 1536, 1024, 1536, wl(p, i, 0), p->in[1] + i * 1024, 0, tile, bid, G, tid);
.LBB0_21:
	s_lshr_b32 s38, s47, 1
	s_bitcmp1_b32 s47, 0
	s_mul_i32 s4, s47, 0x1700000
	s_cselect_b64 s[28:29], -1, 0
	s_add_u32 s20, s2, s4
	s_addc_u32 s21, s3, 0
	s_lshl_b32 s4, s47, 10
	s_lshl_b64 s[22:23], s[4:5], 2
	s_add_u32 s24, s16, s22
	s_addc_u32 s25, s17, s23
	s_mov_b64 s[26:27], -1
	s_and_b64 vcc, exec, s[28:29]
	s_cbranch_vccz .LBB0_28
	s_lshl_b32 s30, s47, 3
	s_lshr_b32 s30, 0xb0803000, s30
	s_add_i32 s30, s30, s92
	s_and_b32 s30, s30, 0xff
	s_cmpk_eq_i32 s34, 0x100
	s_cselect_b32 s30, s30, s92
	s_cmpk_lt_i32 s30, 0x60
	s_cbranch_scc0 .LBB0_35
	s_load_dwordx2 s[26:27], s[36:37], 0x78
	s_mul_i32 s4, s38, 0x180000
	s_lshl_b64 s[28:29], s[4:5], 2
	s_mov_b32 s4, s30
	s_lshl_b32 s30, s30, 8
	s_waitcnt lgkmcnt(0)
	s_add_u32 s26, s26, s28
	s_addc_u32 s27, s27, s29
	v_mov_b64_e32 v[8:9], s[26:27]
	s_branch .LBB0_26

; #define LAS __attribute__((address_space(3)))
; __device__ __forceinline__ bf16_t* wl(PCP p, int i, size_t off) { return (bf16_t*)(p->ws + WS_W + (size_t)i * WL_STRIDE + off); }
; __device__ __forceinline__ void cvt_matrix(const float* W, int K, int N, bf16_t* Wt, const float* gk, int upperm, LAS float* tile, int bid, int G, int tid) {
;     const int nst = N / 256, ntiles = (K / 64) * nst;
;     for (int ti = bid; ti < ntiles; ti += G) {
;         const int kt = ti / nst, ns = ti % nst;
; __device__ __forceinline__ void phase0(PCP p, LAS unsigned char* lds, int bid, int G, int tid) {
;     ...
;     for (int i = 0; i < 4; ++i) {
;         const int j = i >> 1;
;         if ((i & 1) == 0) cvt_matrix(p->in[2] + (size_t)j * 1024 * 2048, 1024, 2048, wl(p, i, 0), p->in[1] + i * 1024, 3, tile, bid, G, tid);
;         else              cvt_matrix(p->in[15] + (size_t)j * 1024 * 1536, 1024, 1536, wl(p, i, 0), p->in[1] + i * 1024, 0, tile, bid, G, tid);
.LBB0_29:
	s_lshl_b32 s39, s47, 3
	s_lshr_b32 s39, 0xb0803000, s39
	s_add_i32 s39, s39, s92
	s_and_b32 s39, s39, 0xff
	s_cmpk_eq_i32 s34, 0x100
	s_cselect_b32 s39, s39, s92
	s_cmpk_lt_i32 s39, 0x80
	s_cbranch_scc0 .LBB0_37
	s_load_dwordx2 s[26:27], s[36:37], 0x10
	s_lshl_b32 s4, s38, 21
	s_lshl_b64 s[28:29], s[4:5], 2
	s_sub_i32 s4, s39, s92
	s_lshl_b32 s4, s4, 10
	v_add_u32_e32 v9, s4, v17
	s_mov_b32 s4, s39
	s_lshl_b32 s39, s39, 8
	s_waitcnt lgkmcnt(0)
	s_add_u32 s26, s26, s28
	s_addc_u32 s27, s27, s29
	s_branch .LBB0_33

; #define LAS __attribute__((address_space(3)))
; __device__ __forceinline__ bf16_t* wl(PCP p, int i, size_t off) { return (bf16_t*)(p->ws + WS_W + (size_t)i * WL_STRIDE + off); }
; __device__ __forceinline__ void cvt_matrix(const float* W, int K, int N, bf16_t* Wt, const float* gk, int upperm, LAS float* tile, int bid, int G, int tid) {
;     const int nst = N / 256, ntiles = (K / 64) * nst;
;     for (int ti = bid; ti < ntiles; ti += G) {
;         const int kt = ti / nst, ns = ti % nst;
; __device__ __forceinline__ void phase0(PCP p, LAS unsigned char* lds, int bid, int G, int tid) {
;     ...
;         else              cvt_matrix(p->in[15] + (size_t)j * 1024 * 1536, 1024, 1536, wl(p, i, 0), p->in[1] + i * 1024, 0, tile, bid, G, tid);
;         cvt_matrix(((i & 1) == 0 ? p->in[14] : p->in[21]) + (size_t)j * 1024 * 1024, 1024, 1024, wl(p, i, 4 * MiB), nullptr, 0, tile, bid, G, tid);
.LBB0_36:
	s_lshl_b32 s39, s47, 3
	s_lshr_b32 s39, 0x5000d080, s39
	s_add_i32 s39, s39, s92
	s_and_b32 s39, s39, 0xff
	s_cmpk_eq_i32 s34, 0x100
	s_cselect_b32 s39, s39, s92
	s_cmp_lt_i32 s39, 64
	s_cbranch_scc1 .LBB0_38
	s_branch .LBB0_40
.LBB0_37:
	s_mov_b64 s[26:27], 0x70
	s_lshl_b32 s39, s47, 3
	s_lshr_b32 s39, 0x5000d080, s39
	s_add_i32 s39, s39, s92
	s_and_b32 s39, s39, 0xff
	s_cmpk_eq_i32 s34, 0x100
	s_cselect_b32 s39, s39, s92
	s_cmp_lt_i32 s39, 64
	s_cbranch_scc0 .LBB0_40
.LBB0_38:
	s_add_u32 s24, s36, s26
	s_addc_u32 s25, s37, s27
	s_load_dwordx2 s[24:25], s[24:25], 0x0
	s_lshl_b32 s4, s38, 20
	s_lshl_b64 s[26:27], s[4:5], 2
	s_mov_b32 s4, s39
	s_lshl_b32 s39, s39, 8
	s_waitcnt lgkmcnt(0)
	s_add_u32 s24, s24, s26
	s_addc_u32 s25, s25, s27
	s_add_u32 s26, s20, 0x400000
	s_addc_u32 s27, s21, 0

; #define LAS __attribute__((address_space(3)))
; __device__ __forceinline__ bf16_t* wl(PCP p, int i, size_t off) { return (bf16_t*)(p->ws + WS_W + (size_t)i * WL_STRIDE + off); }
; __device__ __forceinline__ void cvt_matrix(const float* W, int K, int N, bf16_t* Wt, const float* gk, int upperm, LAS float* tile, int bid, int G, int tid) {
;     const int nst = N / 256, ntiles = (K / 64) * nst;
;     for (int ti = bid; ti < ntiles; ti += G) {
;         const int kt = ti / nst, ns = ti % nst;
;         { const int r = tid >> 3, cb = (tid & 7) * 8; const float s = gk ? gk[kt * 64 + r] : 1.0f;
; __device__ __forceinline__ void phase0(PCP p, LAS unsigned char* lds, int bid, int G, int tid) {
;     ...
;         cvt_matrix(((i & 1) == 0 ? p->in[14] : p->in[21]) + (size_t)j * 1024 * 1024, 1024, 1024, wl(p, i, 4 * MiB), nullptr, 0, tile, bid, G, tid);
;         cvt_matrix(p->in[23] + (size_t)i * 1024 * NUP, 1024, NUP, wl(p, i, 6 * MiB), p->in[22] + i * 1024, 1, tile, bid, G, tid);
.LBB0_40:
	s_andn2_b64 vcc, exec, s[14:15]
	s_cbranch_vccnz .LBB0_50
	s_load_dwordx4 s[28:31], s[36:37], 0xb0
	s_mul_i32 s24, s47, 0x1600000
	s_mul_hi_u32 s25, s47, 0x1600000
	s_lshl_b32 s49, s47, 3
	s_lshr_b32 s49, 0x10c09040, s49
	s_add_i32 s49, s49, s92
	s_and_b32 s49, s49, 0xff
	s_cmpk_eq_i32 s34, 0x100
	s_cselect_b32 s49, s49, s92
	s_sub_i32 s4, s49, s92
	s_lshl_b32 s4, s4, 9
	v_add_u32_e32 v12, s4, v21
	s_lshl_b32 s4, s49, 8
	s_waitcnt lgkmcnt(0)
	s_add_u32 s24, s30, s24
	s_addc_u32 s25, s31, s25
	s_add_u32 s26, s20, 0x600000
	s_addc_u32 s27, s21, 0
	s_add_u32 s22, s28, s22
	s_addc_u32 s23, s29, s23
	s_cmp_lg_u64 s[28:29], 0
	s_cselect_b64 s[28:29], -1, 0
	s_lshl_b32 s48, s34, 9
	s_branch .LBB0_43

; #define LAS __attribute__((address_space(3)))
; __device__ __forceinline__ bf16_t* wl(PCP p, int i, size_t off) { return (bf16_t*)(p->ws + WS_W + (size_t)i * WL_STRIDE + off); }
; __device__ __forceinline__ void cvt_matrix(const float* W, int K, int N, bf16_t* Wt, const float* gk, int upperm, LAS float* tile, int bid, int G, int tid) {
;     const int nst = N / 256, ntiles = (K / 64) * nst;
;     for (int ti = bid; ti < ntiles; ti += G) {
;         const int kt = ti / nst, ns = ti % nst;
; __device__ __forceinline__ void phase0(PCP p, LAS unsigned char* lds, int bid, int G, int tid) {
;     ...
;         cvt_matrix(p->in[26] + (size_t)i * DFF * 1024, DFF, 1024, wl(p, i, 17 * MiB), nullptr, 0, tile, bid, G, tid);
;     }
.LBB0_50:
	s_lshl_b32 s28, s47, 3
	s_lshr_b32 s28, 0xb06030e0, s28
	s_add_i32 s28, s28, s92
	s_and_b32 s28, s28, 0xff
	s_cmpk_eq_i32 s34, 0x100
	s_cselect_b32 s28, s28, s92
	s_cmpk_lt_i32 s28, 0xb0
	s_cbranch_scc0 .LBB0_20
	s_load_dwordx2 s[22:23], s[36:37], 0xd0
	s_mul_i32 s25, s47, 0xb00000
	s_mul_hi_u32 s24, s47, 0xb00000
	s_lshl_b32 s4, s28, 8
	s_waitcnt lgkmcnt(0)
	s_add_u32 s22, s22, s25
	s_addc_u32 s23, s23, s24
	s_add_u32 s20, s20, 0x1100000
	s_addc_u32 s21, s21, 0
